# grid barrier: the workgroup arriving as number nloc-nloc/4 of its XCD issues one early buffer_wbl2 so the last arriver's write-back finds most lines clean (on top of v84)
# baseline (speedup 1.0000x reference)
.LBB0_73:
	s_or_b64 exec, exec, s[12:13]
	v_cvt_f32_u32_e32 v4, v2
	s_waitcnt vmcnt(0)
	v_readfirstlane_b32 s3, v3
	v_sub_u32_e32 v3, 0, v2
	v_rcp_iflag_f32_e32 v4, v4
	v_add_u32_e32 v5, s3, v1
	v_mul_f32_e32 v4, 0x4f7ffffe, v4
	v_cvt_u32_f32_e32 v4, v4
	v_mul_lo_u32 v1, v3, v4
	v_mul_hi_u32 v1, v4, v1
	v_add_u32_e32 v1, v4, v1
	v_mul_hi_u32 v1, v5, v1
	v_mul_lo_u32 v3, v1, v2
	v_sub_u32_e32 v3, v5, v3
	v_add_u32_e32 v4, 1, v1
	v_cmp_ge_u32_e32 vcc, v3, v2
	s_nop 1
	v_cndmask_b32_e32 v1, v1, v4, vcc
	v_sub_u32_e32 v4, v3, v2
	v_cndmask_b32_e32 v3, v3, v4, vcc
	v_add_u32_e32 v4, 1, v1
	v_cmp_ge_u32_e32 vcc, v3, v2
	v_add_u32_e32 v3, 1, v5
	s_nop 0
	v_cndmask_b32_e32 v1, v1, v4, vcc
	v_mul_lo_u32 v4, v2, v1
	v_add_u32_e32 v2, v4, v2
	v_cmp_ne_u32_e32 vcc, v3, v2
	s_and_saveexec_b64 s[10:11], vcc
	s_xor_b64 s[10:11], exec, s[10:11]
	s_cbranch_execz .LBB0_87
	s_waitcnt lgkmcnt(0)
	v_sub_u32_e32 v5, v2, v4
	v_sub_u32_e32 v3, v3, v4
	v_lshrrev_b32_e32 v4, 2, v5
	v_sub_u32_e32 v5, v5, v4
	v_cmp_eq_u32_e32 vcc, v3, v5
	s_cbranch_vccz .Lewb_0
	buffer_wbl2 sc1
.Lewb_0:
	v_mad_u32_u24 v1, v1, v0, v0
	v_mov_b32_e32 v0, 0x7400
	global_load_dword v0, v0, s[96:97] sc1
	s_add_u32 s16, s96, 0x7400
	s_addc_u32 s17, s97, 0
	s_waitcnt vmcnt(0)
	v_cmp_lt_u32_e32 vcc, v0, v1
	s_and_saveexec_b64 s[12:13], vcc
	s_cbranch_execz .LBB0_86
	s_add_u32 s14, s96, 0x4200
	s_addc_u32 s15, s97, 0
	s_mov_b32 s3, 1
	s_mov_b64 s[18:19], 0
	v_mov_b32_e32 v0, 0
	s_branch .LBB0_77

.Lewb_2:
	v_mad_u32_u24 v1, v1, v0, v0
	v_mov_b32_e32 v0, 0x7400
	global_load_dword v0, v0, s[96:97] sc1
	s_add_u32 s16, s96, 0x7400
	s_addc_u32 s17, s97, 0
	s_waitcnt vmcnt(0)
	v_cmp_lt_u32_e32 vcc, v0, v1
	s_and_saveexec_b64 s[12:13], vcc
	s_cbranch_execz .LBB0_414
	s_add_u32 s14, s96, 0x4200
	s_addc_u32 s15, s97, 0
	s_mov_b32 s3, 1
	s_mov_b64 s[20:21], 0
	v_mov_b32_e32 v0, 0
	s_branch .LBB0_405

.LBB0_459:
	s_or_b64 exec, exec, s[10:11]
	v_cvt_f32_u32_e32 v4, v2
	s_waitcnt vmcnt(0)
	v_readfirstlane_b32 s3, v3
	v_sub_u32_e32 v3, 0, v2
	v_rcp_iflag_f32_e32 v4, v4
	v_add_u32_e32 v5, s3, v1
	v_mul_f32_e32 v4, 0x4f7ffffe, v4
	v_cvt_u32_f32_e32 v4, v4
	v_mul_lo_u32 v1, v3, v4
	v_mul_hi_u32 v1, v4, v1
	v_add_u32_e32 v1, v4, v1
	v_mul_hi_u32 v1, v5, v1
	v_mul_lo_u32 v3, v1, v2
	v_sub_u32_e32 v3, v5, v3
	v_add_u32_e32 v4, 1, v1
	v_cmp_ge_u32_e32 vcc, v3, v2
	s_nop 1
	v_cndmask_b32_e32 v1, v1, v4, vcc
	v_sub_u32_e32 v4, v3, v2
	v_cndmask_b32_e32 v3, v3, v4, vcc
	v_add_u32_e32 v4, 1, v1
	v_cmp_ge_u32_e32 vcc, v3, v2
	v_add_u32_e32 v3, 1, v5
	s_nop 0
	v_cndmask_b32_e32 v1, v1, v4, vcc
	v_mul_lo_u32 v4, v2, v1
	v_add_u32_e32 v2, v4, v2
	v_cmp_ne_u32_e32 vcc, v3, v2
	s_and_saveexec_b64 s[8:9], vcc
	s_xor_b64 s[8:9], exec, s[8:9]
	s_cbranch_execz .LBB0_473
	s_waitcnt lgkmcnt(0)
	v_sub_u32_e32 v5, v2, v4
	v_sub_u32_e32 v3, v3, v4
	v_lshrrev_b32_e32 v4, 2, v5
	v_sub_u32_e32 v5, v5, v4
	v_cmp_eq_u32_e32 vcc, v3, v5
	s_cbranch_vccz .Lewb_3
	buffer_wbl2 sc1
.Lewb_3:
	v_mad_u32_u24 v1, v1, v0, v0
	v_mov_b32_e32 v0, 0x7400
	global_load_dword v0, v0, s[96:97] sc1
	s_add_u32 s14, s96, 0x7400
	s_addc_u32 s15, s97, 0
	s_waitcnt vmcnt(0)
	v_cmp_lt_u32_e32 vcc, v0, v1
	s_and_saveexec_b64 s[10:11], vcc
	s_cbranch_execz .LBB0_472
	s_add_u32 s12, s96, 0x4200
	s_addc_u32 s13, s97, 0
	s_mov_b32 s3, 1
	s_mov_b64 s[16:17], 0
	v_mov_b32_e32 v0, 0
	s_branch .LBB0_463

.LBB0_1168:
	s_or_b64 exec, exec, s[14:15]
	v_cvt_f32_u32_e32 v4, v2
	s_waitcnt vmcnt(0)
	v_readfirstlane_b32 s3, v3
	v_sub_u32_e32 v3, 0, v2
	v_rcp_iflag_f32_e32 v4, v4
	v_add_u32_e32 v5, s3, v1
	v_mul_f32_e32 v4, 0x4f7ffffe, v4
	v_cvt_u32_f32_e32 v4, v4
	v_mul_lo_u32 v1, v3, v4
	v_mul_hi_u32 v1, v4, v1
	v_add_u32_e32 v1, v4, v1
	v_mul_hi_u32 v1, v5, v1
	v_mul_lo_u32 v3, v1, v2
	v_sub_u32_e32 v3, v5, v3
	v_add_u32_e32 v4, 1, v1
	v_cmp_ge_u32_e32 vcc, v3, v2
	s_nop 1
	v_cndmask_b32_e32 v1, v1, v4, vcc
	v_sub_u32_e32 v4, v3, v2
	v_cndmask_b32_e32 v3, v3, v4, vcc
	v_add_u32_e32 v4, 1, v1
	v_cmp_ge_u32_e32 vcc, v3, v2
	v_add_u32_e32 v3, 1, v5
	s_nop 0
	v_cndmask_b32_e32 v1, v1, v4, vcc
	v_mul_lo_u32 v4, v2, v1
	v_add_u32_e32 v2, v4, v2
	v_cmp_ne_u32_e32 vcc, v3, v2
	s_and_saveexec_b64 s[10:11], vcc
	s_xor_b64 s[10:11], exec, s[10:11]
	s_cbranch_execz .LBB0_1182
	s_waitcnt lgkmcnt(0)
	v_sub_u32_e32 v5, v2, v4
	v_sub_u32_e32 v3, v3, v4
	v_lshrrev_b32_e32 v4, 2, v5
	v_sub_u32_e32 v5, v5, v4
	v_cmp_eq_u32_e32 vcc, v3, v5
	s_cbranch_vccz .Lewb_8
	buffer_wbl2 sc1
.Lewb_8:
	v_mad_u32_u24 v1, v1, v0, v0
	v_mov_b32_e32 v0, 0x7400
	global_load_dword v0, v0, s[96:97] sc1
	s_add_u32 s20, s96, 0x7400
	s_addc_u32 s21, s97, 0
	s_waitcnt vmcnt(0)
	v_cmp_lt_u32_e32 vcc, v0, v1
	s_and_saveexec_b64 s[14:15], vcc
	s_cbranch_execz .LBB0_1181
	s_add_u32 s16, s96, 0x4200
	s_addc_u32 s17, s97, 0
	s_mov_b32 s3, 1
	s_mov_b64 s[22:23], 0
	v_mov_b32_e32 v0, 0
	s_branch .LBB0_1172

.Lewb_9:
	v_mad_u32_u24 v1, v1, v0, v0
	v_mov_b32_e32 v0, 0x7400
	global_load_dword v0, v0, s[96:97] sc1
	s_add_u32 s18, s96, 0x7400
	s_addc_u32 s19, s97, 0
	s_waitcnt vmcnt(0)
	v_cmp_lt_u32_e32 vcc, v0, v1
	s_and_saveexec_b64 s[14:15], vcc
	s_cbranch_execz .LBB0_1281
	s_add_u32 s16, s96, 0x4200
	s_addc_u32 s17, s97, 0
	s_mov_b32 s3, 1
	s_mov_b64 s[20:21], 0
	v_mov_b32_e32 v0, 0
	s_branch .LBB0_1272

.LBB0_1393:
	s_or_b64 exec, exec, s[14:15]
	v_cvt_f32_u32_e32 v4, v2
	s_waitcnt vmcnt(0)
	v_readfirstlane_b32 s3, v3
	v_sub_u32_e32 v3, 0, v2
	v_rcp_iflag_f32_e32 v4, v4
	v_add_u32_e32 v5, s3, v1
	v_mul_f32_e32 v4, 0x4f7ffffe, v4
	v_cvt_u32_f32_e32 v4, v4
	v_mul_lo_u32 v1, v3, v4
	v_mul_hi_u32 v1, v4, v1
	v_add_u32_e32 v1, v4, v1
	v_mul_hi_u32 v1, v5, v1
	v_mul_lo_u32 v3, v1, v2
	v_sub_u32_e32 v3, v5, v3
	v_add_u32_e32 v4, 1, v1
	v_cmp_ge_u32_e32 vcc, v3, v2
	s_nop 1
	v_cndmask_b32_e32 v1, v1, v4, vcc
	v_sub_u32_e32 v4, v3, v2
	v_cndmask_b32_e32 v3, v3, v4, vcc
	v_add_u32_e32 v4, 1, v1
	v_cmp_ge_u32_e32 vcc, v3, v2
	v_add_u32_e32 v3, 1, v5
	s_nop 0
	v_cndmask_b32_e32 v1, v1, v4, vcc
	v_mul_lo_u32 v4, v2, v1
	v_add_u32_e32 v2, v4, v2
	v_cmp_ne_u32_e32 vcc, v3, v2
	s_and_saveexec_b64 s[12:13], vcc
	s_xor_b64 s[12:13], exec, s[12:13]
	s_cbranch_execz .LBB0_1407
	s_waitcnt lgkmcnt(0)
	v_sub_u32_e32 v5, v2, v4
	v_sub_u32_e32 v3, v3, v4
	v_lshrrev_b32_e32 v4, 2, v5
	v_sub_u32_e32 v5, v5, v4
	v_cmp_eq_u32_e32 vcc, v3, v5
	s_cbranch_vccz .Lewb_10
	buffer_wbl2 sc1
